# P6 fused epilogue: touch second-half x lines via LDS-DMA sink behind first-half loads
# baseline (speedup 1.0000x reference)
.LBB0_2199:
	s_lshr_b32 s0, s4, 4
	s_mulk_i32 s0, 0xc00
	s_ashr_i32 s1, s0, 31
	s_lshl_b32 s20, s42, 5
	s_lshl_b64 s[0:1], s[0:1], 2
	s_add_u32 s0, s80, s0
	s_addc_u32 s1, s81, s1
	s_add_u32 s0, s0, 0x1102000
	s_addc_u32 s1, s1, 0
	s_lshl_b32 s21, s4, 8
	s_lshl_b32 s12, s5, 8
	s_add_i32 s13, s21, s48
	v_readlane_b32 s44, v251, 26
	v_or_b32_e32 v196, s13, v1
	s_ashr_i32 s13, s12, 31
	s_lshl_b32 s14, s42, 2
	v_readlane_b32 s45, v251, 27
	s_add_i32 s14, s14, 0
	s_lshl_b64 s[16:17], s[12:13], 2
	s_mov_b64 s[36:37], s[44:45]
	v_lshrrev_b32_e32 v102, 1, v0
	s_add_u32 s15, s36, s16
	v_and_b32_e32 v202, 24, v102
	s_addc_u32 s17, s37, s17
	s_lshl_b32 s16, s42, 7
	v_or_b32_e32 v102, s20, v202
	s_add_u32 s16, s15, s16
	v_or_b32_e32 v194, s12, v102
	v_mov_b32_e32 v141, 0
	s_addc_u32 s17, s17, 0
	v_lshlrev_b32_e32 v140, 2, v202
	v_ashrrev_i32_e32 v197, 31, v196
	v_ashrrev_i32_e32 v195, 31, v194
	v_lshl_add_u64 v[200:201], s[16:17], 0, v[140:141]
	v_lshlrev_b64 v[140:141], 12, v[196:197]
	v_lshl_add_u64 v[134:135], v[194:195], 2, s[0:1]
	v_lshl_add_u64 v[146:147], v[200:201], 0, v[140:141]
	s_barrier
	global_load_dwordx4 v[102:105], v[134:135], off offset:16
	s_nop 0
	global_load_dwordx4 v[134:137], v[134:135], off
	v_or_b32_e32 v138, 0x80, v194
	global_load_dwordx4 v[204:207], v[146:147], off offset:16
	global_load_dwordx4 v[208:211], v[146:147], off
	v_ashrrev_i32_e32 v139, 31, v138
	v_lshl_add_u64 v[138:139], v[138:139], 2, s[0:1]
	global_load_dwordx4 v[212:215], v[146:147], off offset:512
	global_load_dwordx4 v[142:145], v[138:139], off
	s_nop 0
	global_load_dwordx4 v[138:141], v[138:139], off offset:16
	s_nop 0
	global_load_dwordx4 v[216:219], v[146:147], off offset:528
	v_add_co_u32_e32 v222, vcc, 0x80000, v146
	v_addc_co_u32_e32 v223, vcc, 0, v147, vcc
	s_mov_b32 m0, 0x22800
	s_nop 0
	global_load_lds_dword v[222:223], off
	global_load_lds_dword v[222:223], off offset:512
	v_or_b32_e32 v146, 16, v196
	v_ashrrev_i32_e32 v147, 31, v146
	v_lshlrev_b64 v[146:147], 12, v[146:147]
	v_lshl_add_u64 v[146:147], v[200:201], 0, v[146:147]
	global_load_dwordx4 v[186:189], v[146:147], off offset:16
	global_load_dwordx4 v[190:193], v[146:147], off
	global_load_dwordx4 v[178:181], v[146:147], off offset:528
	global_load_dwordx4 v[182:185], v[146:147], off offset:512
	v_add_co_u32_e32 v222, vcc, 0x80000, v146
	v_addc_co_u32_e32 v223, vcc, 0, v147, vcc
	s_mov_b32 m0, 0x22800
	s_nop 0
	global_load_lds_dword v[222:223], off
	global_load_lds_dword v[222:223], off offset:512
	v_or_b32_e32 v146, 32, v196
	v_ashrrev_i32_e32 v147, 31, v146
	v_lshlrev_b64 v[146:147], 12, v[146:147]
	v_lshl_add_u64 v[146:147], v[200:201], 0, v[146:147]
	global_load_dwordx4 v[170:173], v[146:147], off offset:16
	global_load_dwordx4 v[174:177], v[146:147], off
	global_load_dwordx4 v[162:165], v[146:147], off offset:528
	global_load_dwordx4 v[166:169], v[146:147], off offset:512
	v_add_co_u32_e32 v222, vcc, 0x80000, v146
	v_addc_co_u32_e32 v223, vcc, 0, v147, vcc
	s_mov_b32 m0, 0x22800
	s_nop 0
	global_load_lds_dword v[222:223], off
	global_load_lds_dword v[222:223], off offset:512
	v_or_b32_e32 v146, 48, v196
	v_ashrrev_i32_e32 v147, 31, v146
	v_lshlrev_b64 v[146:147], 12, v[146:147]
	v_lshl_add_u64 v[150:151], v[200:201], 0, v[146:147]
	global_load_dwordx4 v[154:157], v[150:151], off offset:16
	global_load_dwordx4 v[158:161], v[150:151], off
	global_load_dwordx4 v[146:149], v[150:151], off offset:528
	s_nop 0
	v_add_co_u32_e32 v222, vcc, 0x80000, v150
	v_addc_co_u32_e32 v223, vcc, 0, v151, vcc
	s_mov_b32 m0, 0x22800
	s_nop 0
	global_load_lds_dword v[222:223], off
	global_load_lds_dword v[222:223], off offset:512
	global_load_dwordx4 v[150:153], v[150:151], off offset:512
	v_mbcnt_lo_u32_b32 v197, -1, 0
	v_mbcnt_hi_u32_b32 v203, -1, v197
	v_and_b32_e32 v220, 64, v203
	v_xor_b32_e32 v197, 16, v203
	v_add_u32_e32 v220, 64, v220
	v_cmp_lt_i32_e32 vcc, v197, v220
	v_readlane_b32 s52, v251, 34
	v_readlane_b32 s53, v251, 35
	v_cndmask_b32_e32 v197, v203, v197, vcc
	v_lshlrev_b32_e32 v197, 2, v197
	v_readlane_b32 s46, v251, 28
	v_readlane_b32 s47, v251, 29
	v_readlane_b32 s48, v251, 30
	v_readlane_b32 s49, v251, 31
	v_readlane_b32 s50, v251, 32
	v_readlane_b32 s51, v251, 33
	v_readlane_b32 s54, v251, 36
	v_readlane_b32 s55, v251, 37
	v_readlane_b32 s56, v251, 38
	v_readlane_b32 s57, v251, 39
	v_readlane_b32 s58, v251, 40
	v_readlane_b32 s59, v251, 41
	s_waitcnt vmcnt(0)
	v_pk_fma_f32 v[126:127], v[126:127], v[102:103], v[204:205]
	v_pk_fma_f32 v[132:133], v[132:133], v[136:137], v[210:211]
	v_pk_fma_f32 v[130:131], v[130:131], v[134:135], v[208:209]
	v_mul_f32_e32 v205, v133, v133
	v_mul_f32_e32 v204, v131, v131
	v_pk_fma_f32 v[128:129], v[128:129], v[104:105], v[206:207]
	v_pk_fma_f32 v[124:125], v[124:125], v[144:145], v[214:215]
	v_pk_fma_f32 v[122:123], v[122:123], v[142:143], v[212:213]
	v_mul_f32_e32 v206, v127, v127
	v_fmac_f32_e32 v204, v130, v130
	v_fmac_f32_e32 v205, v132, v132
	v_pk_fma_f32 v[118:119], v[118:119], v[138:139], v[216:217]
	v_mul_f32_e32 v208, v123, v123
	v_mul_f32_e32 v209, v125, v125
	v_fmac_f32_e32 v206, v126, v126
	v_add_f32_e32 v204, v204, v205
	v_fmac_f32_e32 v208, v122, v122
	v_fmac_f32_e32 v209, v124, v124
	v_add_f32_e32 v204, v204, v206
	v_mul_f32_e32 v206, v119, v119
	v_pk_fma_f32 v[120:121], v[120:121], v[140:141], v[218:219]
	v_add_f32_e32 v205, v208, v209
	v_fmac_f32_e32 v206, v118, v118
	v_mul_f32_e32 v207, v129, v129
	v_add_f32_e32 v205, v205, v206
	v_mul_f32_e32 v206, v121, v121
	v_fmac_f32_e32 v207, v128, v128
	v_fmac_f32_e32 v206, v120, v120
	v_add_f32_e32 v204, v207, v204
	v_add_f32_e32 v205, v206, v205
	v_add_f32_e32 v205, v204, v205
	ds_bpermute_b32 v206, v197, v205
	v_xor_b32_e32 v204, 32, v203
	v_cmp_lt_i32_e32 vcc, v204, v220
	s_waitcnt lgkmcnt(0)
	v_add_f32_e32 v205, v205, v206
	v_cndmask_b32_e32 v203, v203, v204, vcc
	v_lshlrev_b32_e32 v204, 2, v203
	ds_bpermute_b32 v206, v204, v205
	v_and_b32_e32 v203, 63, v0
	v_cmp_gt_u32_e32 vcc, 16, v203
	s_and_saveexec_b64 s[0:1], vcc
	v_readlane_b32 s52, v251, 24
	v_readlane_b32 s53, v251, 25
	s_cbranch_execz .LBB0_2201
	s_lshl_b32 s15, s38, 10
	s_add_i32 s15, s14, s15
	s_waitcnt lgkmcnt(0)
	v_add_f32_e32 v205, v205, v206
	v_lshl_add_u32 v206, v1, 4, s15
	ds_write_b32 v206, v205
